# each GEMM phase start: touch the phase's weight region (1 dword per 128-B line) to pull it into MALL/L2 ahead of the K-loop DMAs
# baseline (speedup 1.0000x reference)
; #define PG8_STAGE(bufoff, gbase, voff) do { _Pragma("unroll") for (int _i = 0; _i < 2; ++_i) \
;         __builtin_amdgcn_global_load_lds((const unsigned*)((const char*)(gbase) + (voff)[_i]), (PG8_LAS unsigned*)(lds + (bufoff) + ldsw + _i * 8192), 16, 0, 0); } while (0)
; #define PG8_BAR __builtin_amdgcn_s_barrier()
; template <class Epi, class Sched, bool ALIGN_EPI = false, bool SP2 = false>
; __device__ __forceinline__ void gemm_phase(PG8_LAS unsigned char* lds, const Gemm g, const Sched& S, const Epi& E) {
;     ...
;     const int tid = tid_, wid = __builtin_amdgcn_readfirstlane(tid >> 6), lane = tid & 63, wr = wid >> 2, wc = wid & 3, fr = lane & 15, fq = lane >> 4;
;     const int K = g.K, nt = K / BK;
;     unsigned voffA[2], voffB[2];
; #pragma unroll
;     for (int i = 0; i < 2; ++i) { int R, C; stage_rc(tid * 16 + i * 8192, R, C); const int Rb = Epi::PERM ? ((R & ~31) + perm32(R & 31)) : R;
;         voffA[i] = (unsigned)(R * K + C) * 2u; voffB[i] = (unsigned)(Rb * K + C) * 2u; }
;     ...
;         PG8_STAGE(PG8_SB(0, 0), cB, voffB); PG8_STAGE(PG8_SB(0, 1), cB + hstep, voffB); PG8_STAGE(PG8_SA(0, 0), cA, voffA); PG8_STAGE(PG8_SA(0, 1), cA + hstep, voffA);
;         if (wr == 1) PG8_BAR;
.LBB0_198:
	s_mov_b64 s[4:5], s[86:87]
	s_cmp_le_i32 s4, s83
	s_cselect_b64 s[40:41], -1, 0
	s_cmp_lt_i32 s83, s5
	s_cselect_b64 s[4:5], -1, 0
	s_and_b64 s[4:5], s[40:41], s[4:5]
	s_andn2_b64 vcc, exec, s[4:5]
	s_cbranch_vccnz .LBB0_239
	s_mul_i32 s38, s74, 0x6000000
	s_add_u32 vcc_lo, s50, s38
	s_addc_u32 vcc_hi, s51, 0
	s_add_u32 vcc_lo, vcc_lo, 0x1000000
	s_addc_u32 vcc_hi, vcc_hi, 0
	v_readfirstlane_b32 s38, v230
	s_lshr_b32 s38, s38, 6
	s_lshl_b32 s39, s2, 3
	s_add_i32 s39, s39, s38
	s_lshl_b32 s39, s39, 14
	v_and_b32_e32 v240, 63, v230
	v_lshlrev_b32_e32 v240, 7, v240
	v_add_u32_e32 v240, s39, v240
	v_add_u32_e32 v241, 0x2000, v240
	global_load_dword v242, v240, vcc
	global_load_dword v243, v241, vcc
	s_mov_b64 s[4:5], 0
	s_add_u32 s36, s50, s4
	s_addc_u32 s37, s51, s5
	s_mul_i32 s4, s74, 0x6000000
	s_add_u32 s4, s36, s4
	s_addc_u32 s5, s37, 0
	s_add_u32 s68, s4, 0x1000000
	s_addc_u32 s69, s5, 0
	s_add_u32 s22, s36, 0x39000000
	s_addc_u32 s75, s37, 0
	v_readlane_b32 s4, v254, 2
	s_add_u32 s42, s36, 0x300000
	v_mov_b32_e32 v5, v230
	v_readlane_b32 s5, v254, 3
	s_addc_u32 s43, s37, 0
	s_andn2_b64 vcc, exec, s[4:5]
	v_readfirstlane_b32 s4, v5
	s_cbranch_vccnz .LBB0_219
	v_lshlrev_b32_e32 v0, 4, v5
	v_add_u32_e32 v1, 0x2000, v0
	v_ashrrev_i32_e32 v2, 31, v1
	v_lshrrev_b32_e32 v2, 22, v2
	v_add_u32_e32 v2, v1, v2
	v_ashrrev_i32_e32 v4, 10, v2
	v_mul_i32_i24_e32 v2, 0x400, v4
	v_sub_u32_e32 v1, v1, v2
	v_lshrrev_b32_e32 v2, 4, v1
	v_bitop3_b32 v1, v2, v1, 32 bitop3:0x6c
	v_ashrrev_i32_e32 v2, 31, v1
	v_lshrrev_b32_e32 v2, 26, v2
	v_add_u32_e32 v2, v1, v2
	s_waitcnt lgkmcnt(0)
	v_lshlrev_b32_e32 v3, 3, v4
	v_ashrrev_i32_e32 v6, 6, v2
	v_and_b32_e32 v3, -16, v3
	v_add_u32_e32 v3, v6, v3
	v_and_b32_e32 v7, 3, v6
	s_mov_b32 s7, 0xfffe0
	v_lshrrev_b32_e32 v8, 2, v3
	v_lshlrev_b32_e32 v9, 1, v3
	v_and_b32_e32 v2, 0xc0, v2
	v_and_or_b32 v7, v3, s7, v7
	v_and_b32_e32 v8, 4, v8
	v_and_b32_e32 v9, 24, v9
	v_sub_u32_e32 v1, v1, v2
	v_or3_b32 v8, v7, v8, v9
	v_lshlrev_b32_e32 v7, 5, v4
	v_ashrrev_i16_sdwa v1, v224, sext(v1) dst_sel:DWORD dst_unused:UNUSED_PAD src0_sel:DWORD src1_sel:BYTE_0
	v_and_b32_e32 v9, 32, v7
	v_bfe_i32 v7, v1, 0, 16
	v_add_lshl_u32 v1, v9, v7, 1
	v_lshl_add_u32 v128, v8, 12, v1
	v_lshl_add_u32 v130, v3, 12, v1
	v_bfe_i32 v1, v5, 27, 1
	v_lshrrev_b32_e32 v1, 22, v1
	v_add_u32_e32 v1, v0, v1
	v_and_b32_e32 v1, 0xfffffc00, v1
	v_sub_u32_e32 v0, v0, v1
	v_lshrrev_b32_e32 v1, 4, v0
	v_ashrrev_i32_e32 v2, 31, v5
	v_bitop3_b32 v0, v1, v0, 32 bitop3:0x6c
	v_lshrrev_b32_e32 v2, 26, v2
	v_ashrrev_i32_e32 v1, 31, v0
	v_add_u32_e32 v2, v5, v2
	v_lshrrev_b32_e32 v1, 26, v1
	v_ashrrev_i32_e32 v9, 6, v2
	v_add_u32_e32 v1, v0, v1
	v_lshlrev_b32_e32 v2, 3, v9
	v_ashrrev_i32_e32 v8, 6, v1
	v_and_b32_e32 v2, -16, v2
	v_add_u32_e32 v2, v8, v2
	v_and_b32_e32 v3, 3, v8
	v_lshrrev_b32_e32 v10, 2, v2
	v_lshlrev_b32_e32 v11, 1, v2
	v_and_b32_e32 v1, 0xc0, v1
	s_ashr_i32 s6, s4, 6
	v_and_or_b32 v3, v2, s7, v3
	v_and_b32_e32 v10, 4, v10
	v_and_b32_e32 v11, 24, v11
	v_sub_u32_e32 v0, v0, v1
	s_ashr_i32 s5, s4, 8
	s_lshl_b32 s23, s6, 10
	v_or3_b32 v3, v3, v10, v11
	v_lshlrev_b32_e32 v10, 5, v9
	v_ashrrev_i16_sdwa v0, v224, sext(v0) dst_sel:DWORD dst_unused:UNUSED_PAD src0_sel:DWORD src1_sel:BYTE_0
	v_readlane_b32 s8, v254, 55
	v_and_b32_e32 v11, 32, v10
	v_bfe_i32 v10, v0, 0, 16
	v_readlane_b32 s9, v254, 56
	s_add_u32 s10, s68, s8
	v_add_lshl_u32 v0, v11, v10, 1
	s_addc_u32 s11, s69, s9
	s_add_i32 s97, s23, 0
	v_lshl_add_u32 v204, v3, 12, v0
	s_add_i32 m0, s97, 0x10000
	v_lshl_add_u32 v132, v2, 12, v0
	global_load_lds_dwordx4 v204, s[10:11]
	s_add_i32 m0, s97, 0x12000
	s_add_u32 s8, s10, 0x80000
	global_load_lds_dwordx4 v128, s[10:11]
	s_addc_u32 s9, s11, 0
	s_add_i32 m0, s97, 0x14000
	v_mov_b32_e32 v129, v205
	global_load_lds_dwordx4 v204, s[8:9]
	s_add_i32 m0, s97, 0x16000
	v_lshl_add_u64 v[0:1], s[10:11], 0, v[204:205]
	global_load_lds_dwordx4 v128, s[8:9]
	v_readlane_b32 s8, v254, 63
	v_readlane_b32 s9, v255, 0
	s_add_u32 s8, s22, s8
	s_addc_u32 s9, s75, s9
	s_add_i32 s20, s97, 0x2000
	s_mov_b32 m0, s97
	s_add_u32 s16, s8, 0x80000
	global_load_lds_dwordx4 v132, s[8:9]
	s_mov_b32 m0, s20
	s_addc_u32 s17, s9, 0
	s_add_i32 s21, s97, 0x4000
	global_load_lds_dwordx4 v130, s[8:9]
	s_mov_b32 m0, s21
	s_add_i32 s57, s97, 0x6000
	global_load_lds_dwordx4 v132, s[16:17]
	s_mov_b32 m0, s57
	s_cmp_eq_u32 s5, 1
	global_load_lds_dwordx4 v130, s[16:17]
	s_cselect_b64 s[46:47], -1, 0
	s_cmp_lg_u32 s5, 1
	v_lshl_add_u64 v[2:3], s[10:11], 0, v[128:129]
	s_cbranch_scc1 .LBB0_202
	s_barrier

; #define PG8_STAGE(bufoff, gbase, voff) do { _Pragma("unroll") for (int _i = 0; _i < 2; ++_i) \
;         __builtin_amdgcn_global_load_lds((const unsigned*)((const char*)(gbase) + (voff)[_i]), (PG8_LAS unsigned*)(lds + (bufoff) + ldsw + _i * 8192), 16, 0, 0); } while (0)
; #define PG8_BAR __builtin_amdgcn_s_barrier()
; template <class Epi, class Sched, bool ALIGN_EPI = false, bool SP2 = false>
; __device__ __forceinline__ void gemm_phase(PG8_LAS unsigned char* lds, const Gemm g, const Sched& S, const Epi& E) {
;     ...
;     const int tid = tid_, wid = __builtin_amdgcn_readfirstlane(tid >> 6), lane = tid & 63, wr = wid >> 2, wc = wid & 3, fr = lane & 15, fq = lane >> 4;
;     const int K = g.K, nt = K / BK;
;     unsigned voffA[2], voffB[2];
; #pragma unroll
;     for (int i = 0; i < 2; ++i) { int R, C; stage_rc(tid * 16 + i * 8192, R, C); const int Rb = Epi::PERM ? ((R & ~31) + perm32(R & 31)) : R;
;         voffA[i] = (unsigned)(R * K + C) * 2u; voffB[i] = (unsigned)(Rb * K + C) * 2u; }
;     ...
;         PG8_STAGE(PG8_SB(0, 0), cB, voffB); PG8_STAGE(PG8_SB(0, 1), cB + hstep, voffB); PG8_STAGE(PG8_SA(0, 0), cA, voffA); PG8_STAGE(PG8_SA(0, 1), cA + hstep, voffA);
;         if (wr == 1) PG8_BAR;
.LBB0_412:
	s_cmp_le_i32 s86, s20
	s_cselect_b64 s[4:5], -1, 0
	s_and_b64 s[6:7], s[4:5], s[6:7]
	s_andn2_b64 vcc, exec, s[6:7]
	v_readlane_b32 s6, v254, 4
	v_readlane_b32 s7, v254, 5
	s_nop 1
	v_cndmask_b32_e64 v0, 0, 1, s[6:7]
	v_cmp_ne_u32_e64 s[40:41], 1, v0
	s_cbranch_vccnz .LBB0_433
	s_mov_b64 s[6:7], 0
	v_mov_b32_e32 v10, v230
	s_and_b64 vcc, exec, s[40:41]
	v_readfirstlane_b32 s10, v10
	s_cbranch_vccnz .LBB0_433
	s_mul_i32 s38, s74, 0x6000000
	s_add_u32 vcc_lo, s50, s38
	s_addc_u32 vcc_hi, s51, 0
	s_add_u32 vcc_lo, vcc_lo, 0x2800000
	s_addc_u32 vcc_hi, vcc_hi, 0
	v_readfirstlane_b32 s38, v230
	s_lshr_b32 s38, s38, 6
	s_lshl_b32 s39, s2, 3
	s_add_i32 s39, s39, s38
	s_lshl_b32 s39, s39, 14
	v_and_b32_e32 v240, 63, v230
	v_lshlrev_b32_e32 v240, 7, v240
	v_add_u32_e32 v240, s39, v240
	v_add_u32_e32 v241, 0x2000, v240
	global_load_dword v242, v240, vcc
	global_load_dword v243, v241, vcc
	v_lshlrev_b32_e32 v0, 4, v10
	v_add_u32_e32 v1, 0x2000, v0
	v_ashrrev_i32_e32 v2, 31, v1
	v_lshrrev_b32_e32 v2, 22, v2
	v_add_u32_e32 v2, v1, v2
	v_ashrrev_i32_e32 v4, 10, v2
	v_mul_i32_i24_e32 v2, 0x400, v4
	v_sub_u32_e32 v1, v1, v2
	v_lshrrev_b32_e32 v2, 4, v1
	v_bitop3_b32 v1, v2, v1, 32 bitop3:0x6c
	v_ashrrev_i32_e32 v2, 31, v1
	s_add_u32 s8, s50, s6
	v_lshrrev_b32_e32 v2, 26, v2
	s_addc_u32 s9, s51, s7
	s_mul_i32 s6, s74, 0x6000000
	v_add_u32_e32 v2, v1, v2
	s_waitcnt lgkmcnt(0)
	v_lshlrev_b32_e32 v3, 3, v4
	s_add_u32 s6, s8, s6
	v_ashrrev_i32_e32 v5, 6, v2
	v_and_b32_e32 v3, -16, v3
	s_addc_u32 s7, s9, 0
	v_add_u32_e32 v3, v5, v3
	s_add_u32 s20, s6, 0x2800000
	v_and_b32_e32 v6, 3, v5
	s_mov_b32 s6, 0xfffe0
	v_lshrrev_b32_e32 v7, 2, v3
	v_lshlrev_b32_e32 v8, 1, v3
	v_and_b32_e32 v2, 0xc0, v2
	v_and_or_b32 v6, v3, s6, v6
	v_and_b32_e32 v7, 4, v7
	v_and_b32_e32 v8, 24, v8
	v_sub_u32_e32 v1, v1, v2
	v_or3_b32 v7, v6, v7, v8
	v_lshlrev_b32_e32 v6, 5, v4
	v_ashrrev_i16_sdwa v1, v224, sext(v1) dst_sel:DWORD dst_unused:UNUSED_PAD src0_sel:DWORD src1_sel:BYTE_0
	v_and_b32_e32 v8, 32, v6
	v_bfe_i32 v6, v1, 0, 16
	v_add_lshl_u32 v1, v8, v6, 1
	v_lshl_add_u32 v128, v7, 12, v1
	v_lshl_add_u32 v130, v3, 12, v1
	v_bfe_i32 v1, v10, 27, 1
	v_lshrrev_b32_e32 v1, 22, v1
	v_add_u32_e32 v1, v0, v1
	v_and_b32_e32 v1, 0xfffffc00, v1
	v_sub_u32_e32 v0, v0, v1
	v_lshrrev_b32_e32 v1, 4, v0
	v_ashrrev_i32_e32 v2, 31, v10
	v_bitop3_b32 v0, v1, v0, 32 bitop3:0x6c
	v_lshrrev_b32_e32 v2, 26, v2
	v_ashrrev_i32_e32 v1, 31, v0
	v_add_u32_e32 v2, v10, v2
	v_lshrrev_b32_e32 v1, 26, v1
	v_ashrrev_i32_e32 v8, 6, v2
	v_add_u32_e32 v1, v0, v1
	v_lshlrev_b32_e32 v2, 3, v8
	v_ashrrev_i32_e32 v7, 6, v1
	v_and_b32_e32 v2, -16, v2
	v_add_u32_e32 v2, v7, v2
	v_and_b32_e32 v3, 3, v7
	v_lshrrev_b32_e32 v9, 2, v2
	v_lshlrev_b32_e32 v11, 1, v2
	v_and_b32_e32 v1, 0xc0, v1
	s_addc_u32 s21, s7, 0
	s_ashr_i32 s11, s10, 6
	v_and_or_b32 v3, v2, s6, v3
	v_and_b32_e32 v9, 4, v9
	v_and_b32_e32 v11, 24, v11
	v_sub_u32_e32 v0, v0, v1
	s_ashr_i32 s16, s10, 8
	s_lshl_b32 s22, s11, 10
	v_or3_b32 v3, v3, v9, v11
	v_lshlrev_b32_e32 v9, 5, v8
	v_ashrrev_i16_sdwa v0, v224, sext(v0) dst_sel:DWORD dst_unused:UNUSED_PAD src0_sel:DWORD src1_sel:BYTE_0
	v_readlane_b32 s6, v255, 5
	v_and_b32_e32 v11, 32, v9
	v_bfe_i32 v9, v0, 0, 16
	v_readlane_b32 s7, v255, 6
	s_add_u32 s44, s20, s6
	v_add_lshl_u32 v0, v11, v9, 1
	s_addc_u32 s45, s21, s7
	s_add_i32 s23, s22, 0
	v_lshl_add_u32 v204, v3, 12, v0
	s_add_i32 m0, s23, 0x10000
	v_lshl_add_u32 v132, v2, 12, v0
	global_load_lds_dwordx4 v204, s[44:45]
	s_add_i32 m0, s23, 0x12000
	s_add_u32 s6, s44, 0x80000
	global_load_lds_dwordx4 v128, s[44:45]
	s_addc_u32 s7, s45, 0
	s_add_i32 m0, s23, 0x14000
	s_add_i32 s34, s23, 0x2000
	global_load_lds_dwordx4 v204, s[6:7]
	s_add_i32 m0, s23, 0x16000
	s_add_i32 s35, s23, 0x4000
	global_load_lds_dwordx4 v128, s[6:7]
	v_readlane_b32 s6, v255, 7
	s_mov_b32 m0, s23
	v_readlane_b32 s7, v255, 8
	s_add_i32 s36, s23, 0x6000
	v_mov_b32_e32 v129, v205
	s_cmp_eq_u32 s16, 1
	v_lshl_add_u64 v[0:1], s[44:45], 0, v[204:205]
	v_lshl_add_u64 v[2:3], s[44:45], 0, v[128:129]
	global_load_lds_dwordx4 v132, s[6:7]
	s_mov_b32 m0, s34
	s_nop 0
	global_load_lds_dwordx4 v130, s[6:7]
	v_readlane_b32 s6, v255, 9
	s_mov_b32 m0, s35
	v_readlane_b32 s7, v255, 10
	s_nop 4
	global_load_lds_dwordx4 v132, s[6:7]
	s_mov_b32 m0, s36
	s_nop 0
	global_load_lds_dwordx4 v130, s[6:7]
	s_cselect_b64 s[6:7], -1, 0
	s_cmp_lg_u32 s16, 1
	s_cbranch_scc1 .LBB0_416
	s_barrier

; #define PG8_STAGE(bufoff, gbase, voff) do { _Pragma("unroll") for (int _i = 0; _i < 2; ++_i) \
;         __builtin_amdgcn_global_load_lds((const unsigned*)((const char*)(gbase) + (voff)[_i]), (PG8_LAS unsigned*)(lds + (bufoff) + ldsw + _i * 8192), 16, 0, 0); } while (0)
; #define PG8_BAR __builtin_amdgcn_s_barrier()
; template <class Epi, class Sched, bool ALIGN_EPI = false, bool SP2 = false>
; __device__ __forceinline__ void gemm_phase(PG8_LAS unsigned char* lds, const Gemm g, const Sched& S, const Epi& E) {
;     ...
;     const int tid = tid_, wid = __builtin_amdgcn_readfirstlane(tid >> 6), lane = tid & 63, wr = wid >> 2, wc = wid & 3, fr = lane & 15, fq = lane >> 4;
;     const int K = g.K, nt = K / BK;
;     unsigned voffA[2], voffB[2];
; #pragma unroll
;     for (int i = 0; i < 2; ++i) { int R, C; stage_rc(tid * 16 + i * 8192, R, C); const int Rb = Epi::PERM ? ((R & ~31) + perm32(R & 31)) : R;
;         voffA[i] = (unsigned)(R * K + C) * 2u; voffB[i] = (unsigned)(Rb * K + C) * 2u; }
;     ...
;         PG8_STAGE(PG8_SB(0, 0), cB, voffB); PG8_STAGE(PG8_SB(0, 1), cB + hstep, voffB); PG8_STAGE(PG8_SA(0, 0), cA, voffA); PG8_STAGE(PG8_SA(0, 1), cA + hstep, voffA);
;         if (wr == 1) PG8_BAR;
.LBB0_590:
.LBB0_591:
	s_cmp_le_i32 s86, s20
	s_cselect_b64 s[46:47], -1, 0
	s_and_b64 s[4:5], s[46:47], s[4:5]
	s_andn2_b64 vcc, exec, s[4:5]
	s_cbranch_vccnz .LBB0_612
	v_readlane_b32 s6, v254, 52
	s_mov_b64 s[4:5], 0
	v_mov_b32_e32 v10, v230
	v_readlane_b32 s7, v254, 53
	s_andn2_b64 vcc, exec, s[6:7]
	v_readfirstlane_b32 s6, v10
	s_cbranch_vccnz .LBB0_612
	s_mul_i32 s38, s74, 0x6000000
	s_add_u32 vcc_lo, s50, s38
	s_addc_u32 vcc_hi, s51, 0
	s_add_u32 vcc_lo, vcc_lo, 0x3000000
	s_addc_u32 vcc_hi, vcc_hi, 0
	v_readfirstlane_b32 s38, v230
	s_lshr_b32 s38, s38, 6
	s_lshl_b32 s39, s2, 3
	s_add_i32 s39, s39, s38
	s_lshl_b32 s39, s39, 14
	v_and_b32_e32 v240, 63, v230
	v_lshlrev_b32_e32 v240, 7, v240
	v_add_u32_e32 v240, s39, v240
	v_add_u32_e32 v241, 0x2000, v240
	global_load_dword v242, v240, vcc
	global_load_dword v243, v241, vcc
	v_lshlrev_b32_e32 v0, 4, v10
	v_add_u32_e32 v1, 0x2000, v0
	v_ashrrev_i32_e32 v2, 31, v1
	v_lshrrev_b32_e32 v2, 22, v2
	v_add_u32_e32 v2, v1, v2
	v_ashrrev_i32_e32 v4, 10, v2
	v_mul_i32_i24_e32 v2, 0x400, v4
	v_sub_u32_e32 v1, v1, v2
	v_lshrrev_b32_e32 v2, 4, v1
	v_bitop3_b32 v1, v2, v1, 32 bitop3:0x6c
	v_ashrrev_i32_e32 v2, 31, v1
	v_lshrrev_b32_e32 v2, 26, v2
	v_add_u32_e32 v2, v1, v2
	s_waitcnt lgkmcnt(0)
	v_lshlrev_b32_e32 v3, 3, v4
	v_ashrrev_i32_e32 v5, 6, v2
	v_and_b32_e32 v3, -16, v3
	v_add_u32_e32 v3, v5, v3
	v_and_b32_e32 v6, 3, v5
	s_mov_b32 s8, 0xfffe0
	v_lshrrev_b32_e32 v7, 2, v3
	v_lshlrev_b32_e32 v8, 1, v3
	v_and_b32_e32 v2, 0xc0, v2
	v_and_or_b32 v6, v3, s8, v6
	v_and_b32_e32 v7, 4, v7
	v_and_b32_e32 v8, 24, v8
	v_sub_u32_e32 v1, v1, v2
	v_or3_b32 v7, v6, v7, v8
	v_lshlrev_b32_e32 v6, 5, v4
	v_ashrrev_i16_sdwa v1, v224, sext(v1) dst_sel:DWORD dst_unused:UNUSED_PAD src0_sel:DWORD src1_sel:BYTE_0
	v_and_b32_e32 v8, 32, v6
	v_bfe_i32 v6, v1, 0, 16
	v_add_lshl_u32 v1, v8, v6, 1
	v_lshl_add_u32 v128, v7, 12, v1
	v_lshl_add_u32 v130, v3, 12, v1
	v_bfe_i32 v1, v10, 27, 1
	v_lshrrev_b32_e32 v1, 22, v1
	v_add_u32_e32 v1, v0, v1
	v_and_b32_e32 v1, 0xfffffc00, v1
	v_sub_u32_e32 v0, v0, v1
	v_lshrrev_b32_e32 v1, 4, v0
	v_ashrrev_i32_e32 v2, 31, v10
	s_add_u32 s7, s50, s4
	v_bitop3_b32 v0, v1, v0, 32 bitop3:0x6c
	v_lshrrev_b32_e32 v2, 26, v2
	s_addc_u32 s16, s51, s5
	s_mul_i32 s4, s74, 0x6000000
	v_ashrrev_i32_e32 v1, 31, v0
	v_add_u32_e32 v2, v10, v2
	s_add_u32 s4, s7, s4
	v_lshrrev_b32_e32 v1, 26, v1
	v_ashrrev_i32_e32 v8, 6, v2
	s_addc_u32 s5, s16, 0
	v_add_u32_e32 v1, v0, v1
	v_lshlrev_b32_e32 v2, 3, v8
	s_add_u32 s20, s7, 0x39000000
	v_ashrrev_i32_e32 v7, 6, v1
	v_and_b32_e32 v2, -16, v2
	s_addc_u32 s21, s16, 0
	v_add_u32_e32 v2, v7, v2
	v_writelane_b32 v255, s0, 45
	s_add_u32 s22, s4, 0x3000000
	v_and_b32_e32 v3, 3, v7
	v_lshrrev_b32_e32 v9, 2, v2
	v_lshlrev_b32_e32 v11, 1, v2
	v_and_b32_e32 v1, 0xc0, v1
	v_writelane_b32 v255, s1, 46
	s_addc_u32 s23, s5, 0
	s_ashr_i32 s4, s6, 6
	v_and_or_b32 v3, v2, s8, v3
	v_and_b32_e32 v9, 4, v9
	v_and_b32_e32 v11, 24, v11
	v_sub_u32_e32 v0, v0, v1
	s_ashr_i32 s5, s6, 8
	s_lshl_b32 s36, s4, 10
	v_or3_b32 v3, v3, v9, v11
	v_lshlrev_b32_e32 v9, 5, v8
	v_ashrrev_i16_sdwa v0, v224, sext(v0) dst_sel:DWORD dst_unused:UNUSED_PAD src0_sel:DWORD src1_sel:BYTE_0
	v_readlane_b32 s8, v255, 12
	v_and_b32_e32 v11, 32, v9
	v_bfe_i32 v9, v0, 0, 16
	v_readlane_b32 s9, v255, 13
	s_add_u32 s10, s22, s8
	v_add_lshl_u32 v0, v11, v9, 1
	s_addc_u32 s11, s23, s9
	s_add_i32 s37, s36, 0
	v_lshl_add_u32 v204, v3, 12, v0
	s_add_i32 m0, s37, 0x10000
	v_lshl_add_u32 v132, v2, 12, v0
	global_load_lds_dwordx4 v204, s[10:11]
	s_add_i32 m0, s37, 0x12000
	s_add_u32 s8, s10, 0x80000
	global_load_lds_dwordx4 v128, s[10:11]
	s_addc_u32 s9, s11, 0
	s_add_i32 m0, s37, 0x14000
	v_mov_b32_e32 v129, v205
	global_load_lds_dwordx4 v204, s[8:9]
	s_add_i32 m0, s37, 0x16000
	v_lshl_add_u64 v[0:1], s[10:11], 0, v[204:205]
	global_load_lds_dwordx4 v128, s[8:9]
	v_readlane_b32 s8, v255, 18
	v_readlane_b32 s9, v255, 19
	s_add_u32 s8, s20, s8
	s_addc_u32 s9, s21, s9
	s_add_i32 s57, s37, 0x2000
	s_mov_b32 m0, s37
	s_add_u32 s34, s8, 0x80000
	global_load_lds_dwordx4 v132, s[8:9]
	s_mov_b32 m0, s57
	s_addc_u32 s35, s9, 0
	s_add_i32 s75, s37, 0x4000
	global_load_lds_dwordx4 v130, s[8:9]
	s_mov_b32 m0, s75
	s_add_i32 s84, s37, 0x6000
	global_load_lds_dwordx4 v132, s[34:35]
	s_mov_b32 m0, s84
	s_cmp_eq_u32 s5, 1
	global_load_lds_dwordx4 v130, s[34:35]
	s_cselect_b64 s[76:77], -1, 0
	s_cmp_lg_u32 s5, 1
	v_lshl_add_u64 v[2:3], s[10:11], 0, v[128:129]
	s_cbranch_scc1 .LBB0_595
	s_barrier

; #define PG8_STAGE(bufoff, gbase, voff) do { _Pragma("unroll") for (int _i = 0; _i < 2; ++_i) \
;         __builtin_amdgcn_global_load_lds((const unsigned*)((const char*)(gbase) + (voff)[_i]), (PG8_LAS unsigned*)(lds + (bufoff) + ldsw + _i * 8192), 16, 0, 0); } while (0)
; #define PG8_BAR __builtin_amdgcn_s_barrier()
; template <class Epi, class Sched, bool ALIGN_EPI = false, bool SP2 = false>
; __device__ __forceinline__ void gemm_phase(PG8_LAS unsigned char* lds, const Gemm g, const Sched& S, const Epi& E) {
;     ...
;     const int tid = tid_, wid = __builtin_amdgcn_readfirstlane(tid >> 6), lane = tid & 63, wr = wid >> 2, wc = wid & 3, fr = lane & 15, fq = lane >> 4;
;     const int K = g.K, nt = K / BK;
;     unsigned voffA[2], voffB[2];
; #pragma unroll
;     for (int i = 0; i < 2; ++i) { int R, C; stage_rc(tid * 16 + i * 8192, R, C); const int Rb = Epi::PERM ? ((R & ~31) + perm32(R & 31)) : R;
;         voffA[i] = (unsigned)(R * K + C) * 2u; voffB[i] = (unsigned)(Rb * K + C) * 2u; }
;     ...
;         PG8_STAGE(PG8_SB(0, 0), cB, voffB); PG8_STAGE(PG8_SB(0, 1), cB + hstep, voffB); PG8_STAGE(PG8_SA(0, 0), cA, voffA); PG8_STAGE(PG8_SA(0, 1), cA + hstep, voffA);
;         if (wr == 1) PG8_BAR;
.LBB0_687:
.LBB0_688:
	s_cmp_le_i32 s86, s22
	s_cselect_b64 s[4:5], -1, 0
	s_and_b64 s[6:7], s[4:5], s[6:7]
	s_andn2_b64 vcc, exec, s[6:7]
	s_cbranch_vccnz .LBB0_709
	s_mov_b64 s[6:7], 0
	v_mov_b32_e32 v10, v230
	s_and_b64 vcc, exec, s[40:41]
	v_readfirstlane_b32 s10, v10
	s_cbranch_vccnz .LBB0_709
	s_mul_i32 s38, s74, 0x6000000
	s_add_u32 vcc_lo, s50, s38
	s_addc_u32 vcc_hi, s51, 0
	s_add_u32 vcc_lo, vcc_lo, 0x5000000
	s_addc_u32 vcc_hi, vcc_hi, 0
	v_readfirstlane_b32 s38, v230
	s_lshr_b32 s38, s38, 6
	s_lshl_b32 s39, s2, 3
	s_add_i32 s39, s39, s38
	s_lshl_b32 s39, s39, 14
	v_and_b32_e32 v240, 63, v230
	v_lshlrev_b32_e32 v240, 7, v240
	v_add_u32_e32 v240, s39, v240
	v_add_u32_e32 v241, 0x2000, v240
	global_load_dword v242, v240, vcc
	global_load_dword v243, v241, vcc
	v_lshlrev_b32_e32 v0, 4, v10
	v_add_u32_e32 v1, 0x2000, v0
	v_ashrrev_i32_e32 v2, 31, v1
	v_lshrrev_b32_e32 v2, 22, v2
	v_add_u32_e32 v2, v1, v2
	v_ashrrev_i32_e32 v4, 10, v2
	v_mul_i32_i24_e32 v2, 0x400, v4
	v_sub_u32_e32 v1, v1, v2
	v_lshrrev_b32_e32 v2, 4, v1
	s_add_u32 s8, s50, s6
	v_bitop3_b32 v1, v2, v1, 32 bitop3:0x6c
	s_addc_u32 s9, s51, s7
	v_ashrrev_i32_e32 v2, 31, v1
	s_add_u32 s20, s8, 0x25000000
	v_lshrrev_b32_e32 v2, 26, v2
	s_addc_u32 s21, s9, 0
	s_mul_i32 s6, s74, 0x6000000
	v_add_u32_e32 v2, v1, v2
	s_waitcnt lgkmcnt(0)
	v_lshlrev_b32_e32 v3, 3, v4
	s_add_u32 s6, s8, s6
	v_ashrrev_i32_e32 v5, 6, v2
	v_and_b32_e32 v3, -16, v3
	s_addc_u32 s7, s9, 0
	v_add_u32_e32 v3, v5, v3
	s_add_u32 s23, s6, 0x5000000
	v_and_b32_e32 v6, 3, v5
	s_mov_b32 s6, 0x3ffe0
	v_lshrrev_b32_e32 v7, 2, v3
	v_lshlrev_b32_e32 v8, 1, v3
	v_and_b32_e32 v2, 0xc0, v2
	v_and_or_b32 v6, v3, s6, v6
	v_and_b32_e32 v7, 4, v7
	v_and_b32_e32 v8, 24, v8
	v_sub_u32_e32 v1, v1, v2
	v_or3_b32 v7, v6, v7, v8
	v_lshlrev_b32_e32 v6, 5, v4
	v_ashrrev_i16_sdwa v1, v224, sext(v1) dst_sel:DWORD dst_unused:UNUSED_PAD src0_sel:DWORD src1_sel:BYTE_0
	v_and_b32_e32 v8, 32, v6
	v_bfe_i32 v6, v1, 0, 16
	v_add_lshl_u32 v1, v8, v6, 1
	v_lshl_add_u32 v128, v7, 14, v1
	v_lshl_add_u32 v130, v3, 14, v1
	v_bfe_i32 v1, v10, 27, 1
	v_lshrrev_b32_e32 v1, 22, v1
	v_add_u32_e32 v1, v0, v1
	v_and_b32_e32 v1, 0xfffffc00, v1
	v_sub_u32_e32 v0, v0, v1
	v_lshrrev_b32_e32 v1, 4, v0
	v_ashrrev_i32_e32 v2, 31, v10
	v_bitop3_b32 v0, v1, v0, 32 bitop3:0x6c
	v_lshrrev_b32_e32 v2, 26, v2
	v_ashrrev_i32_e32 v1, 31, v0
	v_add_u32_e32 v2, v10, v2
	v_lshrrev_b32_e32 v1, 26, v1
	v_ashrrev_i32_e32 v8, 6, v2
	v_add_u32_e32 v1, v0, v1
	v_lshlrev_b32_e32 v2, 3, v8
	v_ashrrev_i32_e32 v7, 6, v1
	v_and_b32_e32 v2, -16, v2
	v_add_u32_e32 v2, v7, v2
	v_and_b32_e32 v3, 3, v7
	v_lshrrev_b32_e32 v9, 2, v2
	v_lshlrev_b32_e32 v11, 1, v2
	v_and_b32_e32 v1, 0xc0, v1
	s_addc_u32 s34, s7, 0
	s_ashr_i32 s11, s10, 6
	v_and_or_b32 v3, v2, s6, v3
	v_and_b32_e32 v9, 4, v9
	v_and_b32_e32 v11, 24, v11
	v_sub_u32_e32 v0, v0, v1
	s_ashr_i32 s40, s10, 8
	s_lshl_b32 s35, s11, 10
	v_or3_b32 v3, v3, v9, v11
	v_lshlrev_b32_e32 v9, 5, v8
	v_ashrrev_i16_sdwa v0, v224, sext(v0) dst_sel:DWORD dst_unused:UNUSED_PAD src0_sel:DWORD src1_sel:BYTE_0
	v_readlane_b32 s6, v255, 14
	v_and_b32_e32 v11, 32, v9
	v_bfe_i32 v9, v0, 0, 16
	v_readlane_b32 s7, v255, 15
	s_add_u32 s44, s23, s6
	v_add_lshl_u32 v0, v11, v9, 1
	s_addc_u32 s45, s34, s7
	s_add_i32 s36, s35, 0
	v_lshl_add_u32 v204, v3, 14, v0
	s_add_i32 m0, s36, 0x10000
	v_lshl_add_u32 v132, v2, 14, v0
	global_load_lds_dwordx4 v204, s[44:45]
	s_add_i32 m0, s36, 0x12000
	s_add_u32 s6, s44, 0x200000
	global_load_lds_dwordx4 v128, s[44:45]
	s_addc_u32 s7, s45, 0
	s_add_i32 m0, s36, 0x14000
	v_mov_b32_e32 v129, v205
	global_load_lds_dwordx4 v204, s[6:7]
	s_add_i32 m0, s36, 0x16000
	v_lshl_add_u64 v[0:1], s[44:45], 0, v[204:205]
	global_load_lds_dwordx4 v128, s[6:7]
	v_readlane_b32 s6, v255, 22
	v_readlane_b32 s7, v255, 23
	s_add_u32 s16, s20, s6
	s_addc_u32 s17, s21, s7
	s_add_i32 s37, s36, 0x2000
	s_mov_b32 m0, s36
	s_add_u32 s6, s16, 0x200000
	global_load_lds_dwordx4 v132, s[16:17]
	s_mov_b32 m0, s37
	s_addc_u32 s7, s17, 0
	s_add_i32 s57, s36, 0x4000
	global_load_lds_dwordx4 v130, s[16:17]
	s_mov_b32 m0, s57
	s_add_i32 s75, s36, 0x6000
	global_load_lds_dwordx4 v132, s[6:7]
	s_mov_b32 m0, s75
	s_cmp_eq_u32 s40, 1
	global_load_lds_dwordx4 v130, s[6:7]
	s_cselect_b64 s[6:7], -1, 0
	s_cmp_lg_u32 s40, 1
	v_lshl_add_u64 v[2:3], s[44:45], 0, v[128:129]
	s_cbranch_scc1 .LBB0_692
	s_barrier
